# P3 residual epilogue rewritten by hand: x loads issued three 16-row blocks ahead with counted vmcnt, row sums of squares reduced together; plus A3/A1/A6 rewrites
# speedup vs baseline: 1.0068x; 1.0068x over previous
; __device__ __forceinline__ unsigned cvt_pk_bf16(float lo, float hi) { unsigned r; asm volatile("v_cvt_pk_bf16_f32 %0, %1, %2" : "=v"(r) : "v"(lo), "v"(hi)); return r; }
;     __device__ __forceinline__ void operator()(const f32x4 (&acc)[2][2][4][2], const Unit& u, int wr, int wc, int fr, int fq) const {
;         const int row0 = u.pm * BM + wr * 64 + fr; const int col0 = u.pn * BM + wc * 32 + 8 * fq;
; #pragma unroll
;         for (int ai = 0; ai < 2; ++ai)
; #pragma unroll
;             for (int m = 0; m < 4; ++m) { const int row = row0 + ai * HALF + m * 16;
;                 const float* xr = (row < MP ? xp + (size_t)row * DM : xs + (size_t)(row - MP) * DM) + col0;
;                 bf16_t* brow = h2b + (size_t)row * DM + col0; float ss = 0.f;
; #pragma unroll
;                 for (int bj = 0; bj < 2; ++bj) { const f32x4 x0 = *(const f32x4*)(xr + bj * HALF), x1 = *(const f32x4*)(xr + bj * HALF + 4);
;                     const f32x4 v0 = acc[ai][bj][m][0] + x0, v1 = acc[ai][bj][m][1] + x1;
;                     u32x4 w; w.x = cvt_pk_bf16(v0[0], v0[1]); w.y = cvt_pk_bf16(v0[2], v0[3]); w.z = cvt_pk_bf16(v1[0], v1[1]); w.w = cvt_pk_bf16(v1[2], v1[3]);
;                     *(u32x4*)(brow + bj * HALF) = w;
;                     ss += v0[0] * v0[0] + v0[1] * v0[1] + v0[2] * v0[2] + v0[3] * v0[3] + v1[0] * v1[0] + v1[1] * v1[1] + v1[2] * v1[2] + v1[3] * v1[3]; }
;                 ss += __shfl_xor(ss, 16); ss += __shfl_xor(ss, 32);
;                 if (fq == 0) atomicAdd(rowss + row, ss); }
.LBB0_516:
	v_lshl_add_u32 v156, s28, 8, v135
	v_readlane_b32 s52, v249, 14
	v_readlane_b32 s53, v249, 15
	v_readlane_b32 s54, v249, 16
	v_readlane_b32 s55, v249, 17
	v_readlane_b32 s56, v249, 18
	v_readlane_b32 s57, v249, 19
	v_readlane_b32 s58, v249, 20
	v_readlane_b32 s59, v249, 21
	v_readlane_b32 s60, v249, 22
	v_readlane_b32 s61, v249, 23
	v_readlane_b32 s62, v249, 24
	v_readlane_b32 s63, v249, 25
	v_readlane_b32 s64, v249, 26
	v_readlane_b32 s65, v249, 27
	v_readlane_b32 s66, v249, 28
	v_readlane_b32 s67, v249, 29
	v_lshl_or_b32 v158, s26, 8, v167
	v_lshlrev_b32_e32 v160, 12, v156
	v_lshl_add_u32 v160, v158, 2, v160
	v_lshlrev_b32_e32 v161, 11, v156
	v_lshl_add_u32 v161, v158, 1, v161
	v_lshlrev_b32_e32 v146, 2, v156
	v_xor_b32_e32 v159, 16, v209
	v_lshlrev_b32_e32 v159, 2, v159
	v_xor_b32_e32 v234, 32, v209
	v_lshlrev_b32_e32 v234, 2, v234
	global_load_dwordx4 v[172:175], v160, s[52:53]
	global_load_dwordx4 v[176:179], v160, s[52:53] offset:16
	global_load_dwordx4 v[180:183], v160, s[52:53] offset:512
	global_load_dwordx4 v[184:187], v160, s[52:53] offset:528
	v_add_u32_e32 v157, 0x10000, v160
	global_load_dwordx4 v[188:191], v157, s[52:53]
	global_load_dwordx4 v[192:195], v157, s[52:53] offset:16
	global_load_dwordx4 v[196:199], v157, s[52:53] offset:512
	global_load_dwordx4 v[200:203], v157, s[52:53] offset:528
	v_add_u32_e32 v157, 0x20000, v160
	global_load_dwordx4 v[210:213], v157, s[52:53]
	global_load_dwordx4 v[214:217], v157, s[52:53] offset:16
	global_load_dwordx4 v[218:221], v157, s[52:53] offset:512
	global_load_dwordx4 v[222:225], v157, s[52:53] offset:528
	s_waitcnt vmcnt(8)
	v_pk_add_f32 v[124:125], v[124:125], v[172:173]
	v_pk_add_f32 v[126:127], v[126:127], v[174:175]
	v_pk_add_f32 v[120:121], v[120:121], v[176:177]
	v_pk_add_f32 v[122:123], v[122:123], v[178:179]
	v_pk_add_f32 v[116:117], v[116:117], v[180:181]
	v_pk_add_f32 v[118:119], v[118:119], v[182:183]
	v_pk_add_f32 v[112:113], v[112:113], v[184:185]
	v_pk_add_f32 v[114:115], v[114:115], v[186:187]
	v_mul_f32_e32 v226, v125, v125
	v_fmac_f32_e32 v226, v124, v124
	v_fmac_f32_e32 v226, v126, v126
	v_fmac_f32_e32 v226, v127, v127
	v_fmac_f32_e32 v226, v120, v120
	v_fmac_f32_e32 v226, v121, v121
	v_fmac_f32_e32 v226, v122, v122
	v_fmac_f32_e32 v226, v123, v123
	v_mul_f32_e32 v157, v117, v117
	v_fmac_f32_e32 v157, v116, v116
	v_fmac_f32_e32 v157, v118, v118
	v_fmac_f32_e32 v157, v119, v119
	v_fmac_f32_e32 v157, v112, v112
	v_fmac_f32_e32 v157, v113, v113
	v_fmac_f32_e32 v157, v114, v114
	v_fmac_f32_e32 v157, v115, v115
	v_add_f32_e32 v226, v226, v157
	v_cvt_pk_bf16_f32 v172, v124, v125
	v_cvt_pk_bf16_f32 v173, v126, v127
	v_cvt_pk_bf16_f32 v174, v120, v121
	v_cvt_pk_bf16_f32 v175, v122, v123
	v_cvt_pk_bf16_f32 v176, v116, v117
	v_cvt_pk_bf16_f32 v177, v118, v119
	v_cvt_pk_bf16_f32 v178, v112, v113
	v_cvt_pk_bf16_f32 v179, v114, v115
	global_store_dwordx4 v161, v[172:175], s[94:95]
	global_store_dwordx4 v161, v[176:179], s[94:95] offset:256
	s_nop 1
	v_add_u32_e32 v157, 0x30000, v160
	global_load_dwordx4 v[172:175], v157, s[52:53]
	global_load_dwordx4 v[176:179], v157, s[52:53] offset:16
	global_load_dwordx4 v[180:183], v157, s[52:53] offset:512
	global_load_dwordx4 v[184:187], v157, s[52:53] offset:528
	s_waitcnt vmcnt(10)
	v_pk_add_f32 v[108:109], v[108:109], v[188:189]
	v_pk_add_f32 v[110:111], v[110:111], v[190:191]
	v_pk_add_f32 v[104:105], v[104:105], v[192:193]
	v_pk_add_f32 v[106:107], v[106:107], v[194:195]
	v_pk_add_f32 v[100:101], v[100:101], v[196:197]
	v_pk_add_f32 v[102:103], v[102:103], v[198:199]
	v_pk_add_f32 v[96:97], v[96:97], v[200:201]
	v_pk_add_f32 v[98:99], v[98:99], v[202:203]
	v_mul_f32_e32 v227, v109, v109
	v_fmac_f32_e32 v227, v108, v108
	v_fmac_f32_e32 v227, v110, v110
	v_fmac_f32_e32 v227, v111, v111
	v_fmac_f32_e32 v227, v104, v104
	v_fmac_f32_e32 v227, v105, v105
	v_fmac_f32_e32 v227, v106, v106
	v_fmac_f32_e32 v227, v107, v107
	v_mul_f32_e32 v157, v101, v101
	v_fmac_f32_e32 v157, v100, v100
	v_fmac_f32_e32 v157, v102, v102
	v_fmac_f32_e32 v157, v103, v103
	v_fmac_f32_e32 v157, v96, v96
	v_fmac_f32_e32 v157, v97, v97
	v_fmac_f32_e32 v157, v98, v98
	v_fmac_f32_e32 v157, v99, v99
	v_add_f32_e32 v227, v227, v157
	v_cvt_pk_bf16_f32 v188, v108, v109
	v_cvt_pk_bf16_f32 v189, v110, v111
	v_cvt_pk_bf16_f32 v190, v104, v105
	v_cvt_pk_bf16_f32 v191, v106, v107
	v_cvt_pk_bf16_f32 v192, v100, v101
	v_cvt_pk_bf16_f32 v193, v102, v103
	v_cvt_pk_bf16_f32 v194, v96, v97
	v_cvt_pk_bf16_f32 v195, v98, v99
	v_add_u32_e32 v157, 0x8000, v161
	global_store_dwordx4 v157, v[188:191], s[94:95]
	global_store_dwordx4 v157, v[192:195], s[94:95] offset:256
	s_nop 1
	v_add_u32_e32 v157, 0x80000, v160
	global_load_dwordx4 v[188:191], v157, s[52:53]
	global_load_dwordx4 v[192:195], v157, s[52:53] offset:16
	global_load_dwordx4 v[196:199], v157, s[52:53] offset:512
	global_load_dwordx4 v[200:203], v157, s[52:53] offset:528
	s_waitcnt vmcnt(12)
; __device__ __forceinline__ unsigned cvt_pk_bf16(float lo, float hi) { unsigned r; asm volatile("v_cvt_pk_bf16_f32 %0, %1, %2" : "=v"(r) : "v"(lo), "v"(hi)); return r; }
;     __device__ __forceinline__ void operator()(const f32x4 (&acc)[2][2][4][2], const Unit& u, int wr, int wc, int fr, int fq) const {
;     ...
;             for (int m = 0; m < 4; ++m) { const int row = row0 + ai * HALF + m * 16;
;                 const float* xr = (row < MP ? xp + (size_t)row * DM : xs + (size_t)(row - MP) * DM) + col0;
;                 bf16_t* brow = h2b + (size_t)row * DM + col0; float ss = 0.f;
; #pragma unroll
;                 for (int bj = 0; bj < 2; ++bj) { const f32x4 x0 = *(const f32x4*)(xr + bj * HALF), x1 = *(const f32x4*)(xr + bj * HALF + 4);
;                     const f32x4 v0 = acc[ai][bj][m][0] + x0, v1 = acc[ai][bj][m][1] + x1;
;                     u32x4 w; w.x = cvt_pk_bf16(v0[0], v0[1]); w.y = cvt_pk_bf16(v0[2], v0[3]); w.z = cvt_pk_bf16(v1[0], v1[1]); w.w = cvt_pk_bf16(v1[2], v1[3]);
;                     *(u32x4*)(brow + bj * HALF) = w;
;                     ss += v0[0] * v0[0] + v0[1] * v0[1] + v0[2] * v0[2] + v0[3] * v0[3] + v1[0] * v1[0] + v1[1] * v1[1] + v1[2] * v1[2] + v1[3] * v1[3]; }
;                 ss += __shfl_xor(ss, 16); ss += __shfl_xor(ss, 32);
	v_pk_add_f32 v[92:93], v[92:93], v[210:211]
	v_pk_add_f32 v[94:95], v[94:95], v[212:213]
	v_pk_add_f32 v[88:89], v[88:89], v[214:215]
	v_pk_add_f32 v[90:91], v[90:91], v[216:217]
	v_pk_add_f32 v[84:85], v[84:85], v[218:219]
	v_pk_add_f32 v[86:87], v[86:87], v[220:221]
	v_pk_add_f32 v[80:81], v[80:81], v[222:223]
	v_pk_add_f32 v[82:83], v[82:83], v[224:225]
	v_mul_f32_e32 v228, v93, v93
	v_fmac_f32_e32 v228, v92, v92
	v_fmac_f32_e32 v228, v94, v94
	v_fmac_f32_e32 v228, v95, v95
	v_fmac_f32_e32 v228, v88, v88
	v_fmac_f32_e32 v228, v89, v89
	v_fmac_f32_e32 v228, v90, v90
	v_fmac_f32_e32 v228, v91, v91
	v_mul_f32_e32 v157, v85, v85
	v_fmac_f32_e32 v157, v84, v84
	v_fmac_f32_e32 v157, v86, v86
	v_fmac_f32_e32 v157, v87, v87
	v_fmac_f32_e32 v157, v80, v80
	v_fmac_f32_e32 v157, v81, v81
	v_fmac_f32_e32 v157, v82, v82
	v_fmac_f32_e32 v157, v83, v83
	v_add_f32_e32 v228, v228, v157
	v_cvt_pk_bf16_f32 v210, v92, v93
	v_cvt_pk_bf16_f32 v211, v94, v95
	v_cvt_pk_bf16_f32 v212, v88, v89
	v_cvt_pk_bf16_f32 v213, v90, v91
	v_cvt_pk_bf16_f32 v214, v84, v85
	v_cvt_pk_bf16_f32 v215, v86, v87
	v_cvt_pk_bf16_f32 v216, v80, v81
	v_cvt_pk_bf16_f32 v217, v82, v83
	v_add_u32_e32 v157, 0x10000, v161
	global_store_dwordx4 v157, v[210:213], s[94:95]
	global_store_dwordx4 v157, v[214:217], s[94:95] offset:256
	s_nop 1
	v_add_u32_e32 v157, 0x90000, v160
	global_load_dwordx4 v[210:213], v157, s[52:53]
	global_load_dwordx4 v[214:217], v157, s[52:53] offset:16
	global_load_dwordx4 v[218:221], v157, s[52:53] offset:512
	global_load_dwordx4 v[222:225], v157, s[52:53] offset:528
	s_waitcnt vmcnt(12)
	v_pk_add_f32 v[76:77], v[76:77], v[172:173]
	v_pk_add_f32 v[78:79], v[78:79], v[174:175]
	v_pk_add_f32 v[72:73], v[72:73], v[176:177]
	v_pk_add_f32 v[74:75], v[74:75], v[178:179]
	v_pk_add_f32 v[68:69], v[68:69], v[180:181]
	v_pk_add_f32 v[70:71], v[70:71], v[182:183]
	v_pk_add_f32 v[64:65], v[64:65], v[184:185]
	v_pk_add_f32 v[66:67], v[66:67], v[186:187]
	v_mul_f32_e32 v229, v77, v77
	v_fmac_f32_e32 v229, v76, v76
	v_fmac_f32_e32 v229, v78, v78
	v_fmac_f32_e32 v229, v79, v79
	v_fmac_f32_e32 v229, v72, v72
	v_fmac_f32_e32 v229, v73, v73
	v_fmac_f32_e32 v229, v74, v74
	v_fmac_f32_e32 v229, v75, v75
	v_mul_f32_e32 v157, v69, v69
	v_fmac_f32_e32 v157, v68, v68
	v_fmac_f32_e32 v157, v70, v70
	v_fmac_f32_e32 v157, v71, v71
	v_fmac_f32_e32 v157, v64, v64
	v_fmac_f32_e32 v157, v65, v65
	v_fmac_f32_e32 v157, v66, v66
	v_fmac_f32_e32 v157, v67, v67
	v_add_f32_e32 v229, v229, v157
	v_cvt_pk_bf16_f32 v172, v76, v77
	v_cvt_pk_bf16_f32 v173, v78, v79
	v_cvt_pk_bf16_f32 v174, v72, v73
	v_cvt_pk_bf16_f32 v175, v74, v75
	v_cvt_pk_bf16_f32 v176, v68, v69
	v_cvt_pk_bf16_f32 v177, v70, v71
	v_cvt_pk_bf16_f32 v178, v64, v65
	v_cvt_pk_bf16_f32 v179, v66, v67
	v_add_u32_e32 v157, 0x18000, v161
	global_store_dwordx4 v157, v[172:175], s[94:95]
	global_store_dwordx4 v157, v[176:179], s[94:95] offset:256
	s_nop 1
	v_add_u32_e32 v157, 0xa0000, v160
	global_load_dwordx4 v[172:175], v157, s[52:53]
	global_load_dwordx4 v[176:179], v157, s[52:53] offset:16
	global_load_dwordx4 v[180:183], v157, s[52:53] offset:512
	global_load_dwordx4 v[184:187], v157, s[52:53] offset:528
	s_waitcnt vmcnt(12)
	v_pk_add_f32 v[60:61], v[60:61], v[188:189]
	v_pk_add_f32 v[62:63], v[62:63], v[190:191]
	v_pk_add_f32 v[56:57], v[56:57], v[192:193]
	v_pk_add_f32 v[58:59], v[58:59], v[194:195]
	v_pk_add_f32 v[52:53], v[52:53], v[196:197]
	v_pk_add_f32 v[54:55], v[54:55], v[198:199]
	v_pk_add_f32 v[48:49], v[48:49], v[200:201]
	v_pk_add_f32 v[50:51], v[50:51], v[202:203]
	v_mul_f32_e32 v230, v61, v61
	v_fmac_f32_e32 v230, v60, v60
	v_fmac_f32_e32 v230, v62, v62
	v_fmac_f32_e32 v230, v63, v63
	v_fmac_f32_e32 v230, v56, v56
	v_fmac_f32_e32 v230, v57, v57
	v_fmac_f32_e32 v230, v58, v58
	v_fmac_f32_e32 v230, v59, v59
	v_mul_f32_e32 v157, v53, v53
	v_fmac_f32_e32 v157, v52, v52
	v_fmac_f32_e32 v157, v54, v54
	v_fmac_f32_e32 v157, v55, v55
	v_fmac_f32_e32 v157, v48, v48
	v_fmac_f32_e32 v157, v49, v49
	v_fmac_f32_e32 v157, v50, v50
	v_fmac_f32_e32 v157, v51, v51
	v_add_f32_e32 v230, v230, v157
	v_cvt_pk_bf16_f32 v188, v60, v61
	v_cvt_pk_bf16_f32 v189, v62, v63
	v_cvt_pk_bf16_f32 v190, v56, v57
	v_cvt_pk_bf16_f32 v191, v58, v59
	v_cvt_pk_bf16_f32 v192, v52, v53
	v_cvt_pk_bf16_f32 v193, v54, v55
	v_cvt_pk_bf16_f32 v194, v48, v49
	v_cvt_pk_bf16_f32 v195, v50, v51
	v_add_u32_e32 v157, 0x40000, v161
	global_store_dwordx4 v157, v[188:191], s[94:95]
	global_store_dwordx4 v157, v[192:195], s[94:95] offset:256
	s_nop 1
	v_add_u32_e32 v157, 0xb0000, v160
	global_load_dwordx4 v[188:191], v157, s[52:53]
	global_load_dwordx4 v[192:195], v157, s[52:53] offset:16
	global_load_dwordx4 v[196:199], v157, s[52:53] offset:512
	global_load_dwordx4 v[200:203], v157, s[52:53] offset:528
	s_waitcnt vmcnt(12)
; __device__ __forceinline__ unsigned cvt_pk_bf16(float lo, float hi) { unsigned r; asm volatile("v_cvt_pk_bf16_f32 %0, %1, %2" : "=v"(r) : "v"(lo), "v"(hi)); return r; }
;     __device__ __forceinline__ void operator()(const f32x4 (&acc)[2][2][4][2], const Unit& u, int wr, int wc, int fr, int fq) const {
;     ...
;             for (int m = 0; m < 4; ++m) { const int row = row0 + ai * HALF + m * 16;
;                 const float* xr = (row < MP ? xp + (size_t)row * DM : xs + (size_t)(row - MP) * DM) + col0;
;                 bf16_t* brow = h2b + (size_t)row * DM + col0; float ss = 0.f;
; #pragma unroll
;                 for (int bj = 0; bj < 2; ++bj) { const f32x4 x0 = *(const f32x4*)(xr + bj * HALF), x1 = *(const f32x4*)(xr + bj * HALF + 4);
;                     const f32x4 v0 = acc[ai][bj][m][0] + x0, v1 = acc[ai][bj][m][1] + x1;
;                     u32x4 w; w.x = cvt_pk_bf16(v0[0], v0[1]); w.y = cvt_pk_bf16(v0[2], v0[3]); w.z = cvt_pk_bf16(v1[0], v1[1]); w.w = cvt_pk_bf16(v1[2], v1[3]);
;                     *(u32x4*)(brow + bj * HALF) = w;
;                     ss += v0[0] * v0[0] + v0[1] * v0[1] + v0[2] * v0[2] + v0[3] * v0[3] + v1[0] * v1[0] + v1[1] * v1[1] + v1[2] * v1[2] + v1[3] * v1[3]; }
;                 ss += __shfl_xor(ss, 16); ss += __shfl_xor(ss, 32);
;                 if (fq == 0) atomicAdd(rowss + row, ss); }
	v_pk_add_f32 v[44:45], v[44:45], v[210:211]
	v_pk_add_f32 v[46:47], v[46:47], v[212:213]
	v_pk_add_f32 v[40:41], v[40:41], v[214:215]
	v_pk_add_f32 v[42:43], v[42:43], v[216:217]
	v_pk_add_f32 v[36:37], v[36:37], v[218:219]
	v_pk_add_f32 v[38:39], v[38:39], v[220:221]
	v_pk_add_f32 v[32:33], v[32:33], v[222:223]
	v_pk_add_f32 v[34:35], v[34:35], v[224:225]
	v_mul_f32_e32 v231, v45, v45
	v_fmac_f32_e32 v231, v44, v44
	v_fmac_f32_e32 v231, v46, v46
	v_fmac_f32_e32 v231, v47, v47
	v_fmac_f32_e32 v231, v40, v40
	v_fmac_f32_e32 v231, v41, v41
	v_fmac_f32_e32 v231, v42, v42
	v_fmac_f32_e32 v231, v43, v43
	v_mul_f32_e32 v157, v37, v37
	v_fmac_f32_e32 v157, v36, v36
	v_fmac_f32_e32 v157, v38, v38
	v_fmac_f32_e32 v157, v39, v39
	v_fmac_f32_e32 v157, v32, v32
	v_fmac_f32_e32 v157, v33, v33
	v_fmac_f32_e32 v157, v34, v34
	v_fmac_f32_e32 v157, v35, v35
	v_add_f32_e32 v231, v231, v157
	v_cvt_pk_bf16_f32 v210, v44, v45
	v_cvt_pk_bf16_f32 v211, v46, v47
	v_cvt_pk_bf16_f32 v212, v40, v41
	v_cvt_pk_bf16_f32 v213, v42, v43
	v_cvt_pk_bf16_f32 v214, v36, v37
	v_cvt_pk_bf16_f32 v215, v38, v39
	v_cvt_pk_bf16_f32 v216, v32, v33
	v_cvt_pk_bf16_f32 v217, v34, v35
	v_add_u32_e32 v157, 0x48000, v161
	global_store_dwordx4 v157, v[210:213], s[94:95]
	global_store_dwordx4 v157, v[214:217], s[94:95] offset:256
	s_waitcnt vmcnt(8)
	v_pk_add_f32 v[28:29], v[28:29], v[172:173]
	v_pk_add_f32 v[30:31], v[30:31], v[174:175]
	v_pk_add_f32 v[24:25], v[24:25], v[176:177]
	v_pk_add_f32 v[26:27], v[26:27], v[178:179]
	v_pk_add_f32 v[20:21], v[20:21], v[180:181]
	v_pk_add_f32 v[22:23], v[22:23], v[182:183]
	v_pk_add_f32 v[16:17], v[16:17], v[184:185]
	v_pk_add_f32 v[18:19], v[18:19], v[186:187]
	v_mul_f32_e32 v232, v29, v29
	v_fmac_f32_e32 v232, v28, v28
	v_fmac_f32_e32 v232, v30, v30
	v_fmac_f32_e32 v232, v31, v31
	v_fmac_f32_e32 v232, v24, v24
	v_fmac_f32_e32 v232, v25, v25
	v_fmac_f32_e32 v232, v26, v26
	v_fmac_f32_e32 v232, v27, v27
	v_mul_f32_e32 v157, v21, v21
	v_fmac_f32_e32 v157, v20, v20
	v_fmac_f32_e32 v157, v22, v22
	v_fmac_f32_e32 v157, v23, v23
	v_fmac_f32_e32 v157, v16, v16
	v_fmac_f32_e32 v157, v17, v17
	v_fmac_f32_e32 v157, v18, v18
	v_fmac_f32_e32 v157, v19, v19
	v_add_f32_e32 v232, v232, v157
	v_cvt_pk_bf16_f32 v172, v28, v29
	v_cvt_pk_bf16_f32 v173, v30, v31
	v_cvt_pk_bf16_f32 v174, v24, v25
	v_cvt_pk_bf16_f32 v175, v26, v27
	v_cvt_pk_bf16_f32 v176, v20, v21
	v_cvt_pk_bf16_f32 v177, v22, v23
	v_cvt_pk_bf16_f32 v178, v16, v17
	v_cvt_pk_bf16_f32 v179, v18, v19
	v_add_u32_e32 v157, 0x50000, v161
	global_store_dwordx4 v157, v[172:175], s[94:95]
	global_store_dwordx4 v157, v[176:179], s[94:95] offset:256
	s_waitcnt vmcnt(4)
	v_pk_add_f32 v[12:13], v[12:13], v[188:189]
	v_pk_add_f32 v[14:15], v[14:15], v[190:191]
	v_pk_add_f32 v[8:9], v[8:9], v[192:193]
	v_pk_add_f32 v[10:11], v[10:11], v[194:195]
	v_pk_add_f32 v[4:5], v[4:5], v[196:197]
	v_pk_add_f32 v[6:7], v[6:7], v[198:199]
	v_pk_add_f32 v[0:1], v[0:1], v[200:201]
	v_pk_add_f32 v[2:3], v[2:3], v[202:203]
	v_mul_f32_e32 v233, v13, v13
	v_fmac_f32_e32 v233, v12, v12
	v_fmac_f32_e32 v233, v14, v14
	v_fmac_f32_e32 v233, v15, v15
	v_fmac_f32_e32 v233, v8, v8
	v_fmac_f32_e32 v233, v9, v9
	v_fmac_f32_e32 v233, v10, v10
	v_fmac_f32_e32 v233, v11, v11
	v_mul_f32_e32 v157, v5, v5
	v_fmac_f32_e32 v157, v4, v4
	v_fmac_f32_e32 v157, v6, v6
	v_fmac_f32_e32 v157, v7, v7
	v_fmac_f32_e32 v157, v0, v0
	v_fmac_f32_e32 v157, v1, v1
	v_fmac_f32_e32 v157, v2, v2
	v_fmac_f32_e32 v157, v3, v3
	v_add_f32_e32 v233, v233, v157
	v_cvt_pk_bf16_f32 v188, v12, v13
	v_cvt_pk_bf16_f32 v189, v14, v15
	v_cvt_pk_bf16_f32 v190, v8, v9
	v_cvt_pk_bf16_f32 v191, v10, v11
	v_cvt_pk_bf16_f32 v192, v4, v5
	v_cvt_pk_bf16_f32 v193, v6, v7
	v_cvt_pk_bf16_f32 v194, v0, v1
	v_cvt_pk_bf16_f32 v195, v2, v3
	v_add_u32_e32 v157, 0x58000, v161
	global_store_dwordx4 v157, v[188:191], s[94:95]
	global_store_dwordx4 v157, v[192:195], s[94:95] offset:256
	ds_bpermute_b32 v0, v159, v226
	ds_bpermute_b32 v1, v159, v227
	ds_bpermute_b32 v2, v159, v228
	ds_bpermute_b32 v3, v159, v229
	ds_bpermute_b32 v4, v159, v230
	ds_bpermute_b32 v5, v159, v231
	ds_bpermute_b32 v6, v159, v232
	ds_bpermute_b32 v7, v159, v233
	s_waitcnt lgkmcnt(0)
	v_add_f32_e32 v226, v226, v0
	v_add_f32_e32 v227, v227, v1
	v_add_f32_e32 v228, v228, v2
	v_add_f32_e32 v229, v229, v3
	v_add_f32_e32 v230, v230, v4
	v_add_f32_e32 v231, v231, v5
	v_add_f32_e32 v232, v232, v6
	v_add_f32_e32 v233, v233, v7
	ds_bpermute_b32 v0, v234, v226
	ds_bpermute_b32 v1, v234, v227
	ds_bpermute_b32 v2, v234, v228
	ds_bpermute_b32 v3, v234, v229
	ds_bpermute_b32 v4, v234, v230
	ds_bpermute_b32 v5, v234, v231
	ds_bpermute_b32 v6, v234, v232
	ds_bpermute_b32 v7, v234, v233
	s_waitcnt lgkmcnt(0)
	v_add_f32_e32 v226, v226, v0
	v_add_f32_e32 v227, v227, v1
	v_add_f32_e32 v228, v228, v2
	v_add_f32_e32 v229, v229, v3
	v_add_f32_e32 v230, v230, v4
	v_add_f32_e32 v231, v231, v5
	v_add_f32_e32 v232, v232, v6
	v_add_f32_e32 v233, v233, v7
	s_mov_b64 exec, s[4:5]
	global_atomic_add_f32 v146, v226, s[10:11]
	global_atomic_add_f32 v146, v227, s[10:11] offset:64
	global_atomic_add_f32 v146, v228, s[10:11] offset:128
	global_atomic_add_f32 v146, v229, s[10:11] offset:192
	global_atomic_add_f32 v146, v230, s[10:11] offset:512
	global_atomic_add_f32 v146, v231, s[10:11] offset:576
	global_atomic_add_f32 v146, v232, s[10:11] offset:640
	global_atomic_add_f32 v146, v233, s[10:11] offset:704
	s_mov_b64 exec, -1
